# grid barrier arrival made hierarchical: 8 group counters (wg&7) with returning atomic, last arriver bumps global counter; pollers wait for 8*idx
# speedup vs baseline: 1.0641x; 1.0133x over previous
; __global__ void __launch_bounds__(NT) mega(P p, int lo, int hi) {
;   extern __shared__ __attribute__((aligned(16))) char smem[];
;   const int bid = blockIdx.x, nb = gridDim.x;
_Z4mega1Pii:
	s_load_dwordx2 s[4:5], s[0:1], 0xd8
	s_load_dwordx8 s[20:27], s[0:1], 0x0
	s_load_dwordx4 s[28:31], s[0:1], 0x38
	s_load_dwordx16 s[36:51], s[0:1], 0x98
	v_writelane_b32 v251, s2, 0
	s_add_u32 s2, s0, 0xe0
	s_addc_u32 s3, s1, 0
	s_waitcnt lgkmcnt(0)
	s_load_dword s98, s[0:1], 0xe0
	s_mov_b32 s99, 0
	v_readlane_b32 s100, v251, 0
	s_cmp_lg_u32 s100, 0
	s_cbranch_scc1 .Lgs_noinit
	v_and_b32_e32 v2, 0x3ff, v0
	v_cmp_gt_u32_e32 vcc, 9, v2
	s_add_u32 s100, s50, 0x3940000
	s_addc_u32 s101, s51, 0
	v_lshlrev_b32_e32 v2, 12, v2
	v_mov_b32_e32 v3, 0
	s_and_saveexec_b64 vcc, vcc
	s_cbranch_execz .Lgs_initdone
	global_atomic_swap v2, v3, s[100:101]
	s_waitcnt vmcnt(0)

; #define RUNPH(n, body)                                   \
;   if (DUP_PH == (n) && DUP_PH == 10) { phase10<true>(p, smem, bid, nb); __syncthreads(); } \
;   if (PHON(n) && lo <= (n) && (n) < hi) { for (int rep = 0; rep < ((DUP_PH == (n) && DUP_PH != 10) ? hi - 9 : 1); rep++) { body; __syncthreads(); } }         \
;   if (lo <= (n) && (n) + 1 < hi) cg::this_grid().sync();
; __global__ void __launch_bounds__(NT) mega(P p, int lo, int hi) {
;     ...
;   RUNPH(1, phase1(p, smem, bid, nb))
.LBB0_109:
	s_load_dwordx2 s[2:3], s[0:1], 0xd8
	s_waitcnt lgkmcnt(0)
	s_cmp_gt_i32 s3, 2
	s_cselect_b64 s[2:3], -1, 0
	s_and_b64 s[4:5], s[4:5], s[2:3]
	s_andn2_b64 vcc, exec, s[4:5]
	s_cbranch_vccnz .LBB0_121
	v_and_b32_e32 v1, 0x3fffffff, v0
	v_cmp_eq_u32_e32 vcc, 0, v1
	s_barrier
	s_add_i32 s99, s99, 1
	s_and_saveexec_b64 s[4:5], vcc
	s_cbranch_execz .Lgs1_done
	v_readlane_b32 s6, v251, 15
	v_readlane_b32 s7, v251, 16
	s_add_u32 s6, s6, 0x3940000
	s_addc_u32 s7, s7, 0
	buffer_wbl2 sc1
	s_waitcnt vmcnt(0)
	v_readlane_b32 s8, v251, 0
	s_and_b32 s8, s8, 7
	s_sub_i32 s9, s98, s8
	s_add_i32 s9, s9, 7
	s_lshr_b32 s9, s9, 3
	s_lshl_b32 s8, s8, 12
	s_add_i32 s8, s8, 0x1000
	v_mov_b32_e32 v1, s8
	v_mov_b32_e32 v2, 1
	global_atomic_add v2, v1, v2, s[6:7] sc0
	s_mul_i32 s8, s99, s9
	s_waitcnt vmcnt(0)
	v_readfirstlane_b32 s9, v2
	s_add_i32 s9, s9, 1
	v_mov_b32_e32 v1, 0
	v_mov_b32_e32 v2, 1
	s_cmp_lg_u32 s9, s8
	s_cbranch_scc1 .Lgs1_nolast
	global_atomic_add v1, v2, s[6:7]
.Lgs1_nolast:
	s_lshl_b32 s8, s99, 3

; #define RUNPH(n, body)                                   \
;   if (DUP_PH == (n) && DUP_PH == 10) { phase10<true>(p, smem, bid, nb); __syncthreads(); } \
;   if (PHON(n) && lo <= (n) && (n) < hi) { for (int rep = 0; rep < ((DUP_PH == (n) && DUP_PH != 10) ? hi - 9 : 1); rep++) { body; __syncthreads(); } }         \
;   if (lo <= (n) && (n) + 1 < hi) cg::this_grid().sync();
; __global__ void __launch_bounds__(NT) mega(P p, int lo, int hi) {
;     ...
;   RUNPH(2, phase2(p, smem, bid, nb))
.LBB0_321:
	s_load_dwordx16 s[4:19], s[0:1], 0x58
	s_waitcnt lgkmcnt(0)
	v_writelane_b32 v251, s4, 29
	s_nop 1
	v_writelane_b32 v251, s5, 30
	v_writelane_b32 v251, s6, 31
	v_writelane_b32 v251, s7, 32
	v_writelane_b32 v251, s8, 33
	v_writelane_b32 v251, s9, 34
	v_writelane_b32 v251, s10, 35
	v_writelane_b32 v251, s11, 36
	v_writelane_b32 v251, s12, 37
	v_writelane_b32 v251, s13, 38
	v_writelane_b32 v251, s14, 39
	v_writelane_b32 v251, s15, 40
	v_writelane_b32 v251, s16, 41
	v_writelane_b32 v251, s17, 42
	v_writelane_b32 v251, s18, 43
	v_writelane_b32 v251, s19, 44
	s_nop 0
	v_readlane_b32 s0, v251, 21
	v_readlane_b32 s1, v251, 22
	s_cmp_gt_i32 s1, 3
	s_cselect_b64 s[0:1], -1, 0
	s_and_b64 s[2:3], s[28:29], s[0:1]
	s_andn2_b64 vcc, exec, s[2:3]
	s_cbranch_vccnz .LBB0_333
	v_and_b32_e32 v1, 0x3fffffff, v0
	v_cmp_eq_u32_e32 vcc, 0, v1
	s_barrier
	s_add_i32 s99, s99, 1
	s_and_saveexec_b64 s[2:3], vcc
	s_cbranch_execz .Lgs2_done
	v_readlane_b32 s4, v251, 15
	v_readlane_b32 s5, v251, 16
	s_add_u32 s4, s4, 0x3940000
	s_addc_u32 s5, s5, 0
	buffer_wbl2 sc1
	s_waitcnt vmcnt(0)
	v_readlane_b32 s6, v251, 0
	s_and_b32 s6, s6, 7
	s_sub_i32 s7, s98, s6
	s_add_i32 s7, s7, 7
	s_lshr_b32 s7, s7, 3
	s_lshl_b32 s6, s6, 12
	s_add_i32 s6, s6, 0x1000
	v_mov_b32_e32 v1, s6
	v_mov_b32_e32 v2, 1
	global_atomic_add v2, v1, v2, s[4:5] sc0
	s_mul_i32 s6, s99, s7
	s_waitcnt vmcnt(0)
	v_readfirstlane_b32 s7, v2
	s_add_i32 s7, s7, 1
	v_mov_b32_e32 v1, 0
	v_mov_b32_e32 v2, 1
	s_cmp_lg_u32 s7, s6
	s_cbranch_scc1 .Lgs2_nolast
	global_atomic_add v1, v2, s[4:5]
.Lgs2_nolast:
	s_lshl_b32 s6, s99, 3

; #define RUNPH(n, body)                                   \
;   if (DUP_PH == (n) && DUP_PH == 10) { phase10<true>(p, smem, bid, nb); __syncthreads(); } \
;   if (PHON(n) && lo <= (n) && (n) < hi) { for (int rep = 0; rep < ((DUP_PH == (n) && DUP_PH != 10) ? hi - 9 : 1); rep++) { body; __syncthreads(); } }         \
;   if (lo <= (n) && (n) + 1 < hi) cg::this_grid().sync();
; __global__ void __launch_bounds__(NT) mega(P p, int lo, int hi) {
;     ...
;   RUNPH(3, phase3(p, smem, bid, nb))
.LBB0_528:
	v_readlane_b32 s0, v251, 21
	v_readlane_b32 s1, v251, 22
	s_cmp_gt_i32 s1, 4
	s_cselect_b64 s[0:1], -1, 0
	s_and_b64 s[2:3], s[18:19], s[0:1]
	s_andn2_b64 vcc, exec, s[2:3]
	s_cbranch_vccnz .LBB0_540
	v_and_b32_e32 v1, 0x3fffffff, v0
	v_cmp_eq_u32_e32 vcc, 0, v1
	s_barrier
	s_add_i32 s99, s99, 1
	s_and_saveexec_b64 s[2:3], vcc
	s_cbranch_execz .Lgs3_done
	v_readlane_b32 s4, v251, 15
	v_readlane_b32 s5, v251, 16
	s_add_u32 s4, s4, 0x3940000
	s_addc_u32 s5, s5, 0
	buffer_wbl2 sc1
	s_waitcnt vmcnt(0)
	v_readlane_b32 s6, v251, 0
	s_and_b32 s6, s6, 7
	s_sub_i32 s7, s98, s6
	s_add_i32 s7, s7, 7
	s_lshr_b32 s7, s7, 3
	s_lshl_b32 s6, s6, 12
	s_add_i32 s6, s6, 0x1000
	v_mov_b32_e32 v1, s6
	v_mov_b32_e32 v2, 1
	global_atomic_add v2, v1, v2, s[4:5] sc0
	s_mul_i32 s6, s99, s7
	s_waitcnt vmcnt(0)
	v_readfirstlane_b32 s7, v2
	s_add_i32 s7, s7, 1
	v_mov_b32_e32 v1, 0
	v_mov_b32_e32 v2, 1
	s_cmp_lg_u32 s7, s6
	s_cbranch_scc1 .Lgs3_nolast
	global_atomic_add v1, v2, s[4:5]

; #define RUNPH(n, body)                                   \
;   if (DUP_PH == (n) && DUP_PH == 10) { phase10<true>(p, smem, bid, nb); __syncthreads(); } \
;   if (PHON(n) && lo <= (n) && (n) < hi) { for (int rep = 0; rep < ((DUP_PH == (n) && DUP_PH != 10) ? hi - 9 : 1); rep++) { body; __syncthreads(); } }         \
;   if (lo <= (n) && (n) + 1 < hi) cg::this_grid().sync();
; __global__ void __launch_bounds__(NT) mega(P p, int lo, int hi) {
;     ...
;   RUNPH(4, phase4(p, smem, bid, nb, 8, 16))
.LBB0_718:
	v_readlane_b32 s0, v251, 21
	v_readlane_b32 s1, v251, 22
	s_cmp_gt_i32 s1, 5
	s_cselect_b64 s[0:1], -1, 0
	s_and_b64 s[2:3], s[6:7], s[0:1]
	s_andn2_b64 vcc, exec, s[2:3]
	s_cbranch_vccnz .LBB0_730
	v_and_b32_e32 v1, 0x3fffffff, v0
	v_cmp_eq_u32_e32 vcc, 0, v1
	s_barrier
	s_add_i32 s99, s99, 1
	s_and_saveexec_b64 s[2:3], vcc
	s_cbranch_execz .Lgs4_done
	v_readlane_b32 s4, v251, 15
	v_readlane_b32 s5, v251, 16
	s_add_u32 s4, s4, 0x3940000
	s_addc_u32 s5, s5, 0
	buffer_wbl2 sc1
	s_waitcnt vmcnt(0)
	v_readlane_b32 s6, v251, 0
	s_and_b32 s6, s6, 7
	s_sub_i32 s7, s98, s6
	s_add_i32 s7, s7, 7
	s_lshr_b32 s7, s7, 3
	s_lshl_b32 s6, s6, 12
	s_add_i32 s6, s6, 0x1000
	v_mov_b32_e32 v1, s6
	v_mov_b32_e32 v2, 1
	global_atomic_add v2, v1, v2, s[4:5] sc0
	s_mul_i32 s6, s99, s7
	s_waitcnt vmcnt(0)
	v_readfirstlane_b32 s7, v2
	s_add_i32 s7, s7, 1
	v_mov_b32_e32 v1, 0
	v_mov_b32_e32 v2, 1
	s_cmp_lg_u32 s7, s6
	s_cbranch_scc1 .Lgs4_nolast
	global_atomic_add v1, v2, s[4:5]

; #define RUNPH(n, body)                                   \
;   if (DUP_PH == (n) && DUP_PH == 10) { phase10<true>(p, smem, bid, nb); __syncthreads(); } \
;   if (PHON(n) && lo <= (n) && (n) < hi) { for (int rep = 0; rep < ((DUP_PH == (n) && DUP_PH != 10) ? hi - 9 : 1); rep++) { body; __syncthreads(); } }         \
;   if (lo <= (n) && (n) + 1 < hi) cg::this_grid().sync();
; __global__ void __launch_bounds__(NT) mega(P p, int lo, int hi) {
;     ...
;   RUNPH(5, phase5(p, smem, bid, nb))
.LBB0_789:
	v_readlane_b32 s0, v251, 21
	v_readlane_b32 s1, v251, 22
	s_cmp_gt_i32 s1, 6
	s_cselect_b64 s[0:1], -1, 0
	s_and_b64 s[2:3], s[2:3], s[0:1]
	s_andn2_b64 vcc, exec, s[2:3]
	s_cbranch_vccnz .LBB0_801
	v_and_b32_e32 v2, 0x3fffffff, v0
	v_cmp_eq_u32_e32 vcc, 0, v2
	s_barrier
	s_add_i32 s99, s99, 1
	s_and_saveexec_b64 s[2:3], vcc
	s_cbranch_execz .Lgs5_done
	v_readlane_b32 s4, v251, 15
	v_readlane_b32 s5, v251, 16
	s_add_u32 s4, s4, 0x3940000
	s_addc_u32 s5, s5, 0
	buffer_wbl2 sc1
	s_waitcnt vmcnt(0)
	v_readlane_b32 s6, v251, 0
	s_and_b32 s6, s6, 7
	s_sub_i32 s7, s98, s6
	s_add_i32 s7, s7, 7
	s_lshr_b32 s7, s7, 3
	s_lshl_b32 s6, s6, 12
	s_add_i32 s6, s6, 0x1000
	v_mov_b32_e32 v2, s6
	v_mov_b32_e32 v3, 1
	global_atomic_add v3, v2, v3, s[4:5] sc0
	s_mul_i32 s6, s99, s7
	s_waitcnt vmcnt(0)
	v_readfirstlane_b32 s7, v3
	s_add_i32 s7, s7, 1
	v_mov_b32_e32 v2, 0
	v_mov_b32_e32 v3, 1
	s_cmp_lg_u32 s7, s6
	s_cbranch_scc1 .Lgs5_nolast
	global_atomic_add v2, v3, s[4:5]

; #define RUNPH(n, body)                                   \
;   if (DUP_PH == (n) && DUP_PH == 10) { phase10<true>(p, smem, bid, nb); __syncthreads(); } \
;   if (PHON(n) && lo <= (n) && (n) < hi) { for (int rep = 0; rep < ((DUP_PH == (n) && DUP_PH != 10) ? hi - 9 : 1); rep++) { body; __syncthreads(); } }         \
;   if (lo <= (n) && (n) + 1 < hi) cg::this_grid().sync();
; __global__ void __launch_bounds__(NT) mega(P p, int lo, int hi) {
;     ...
;   RUNPH(6, phase6(p, smem, bid, nb))
.LBB0_811:
	v_readlane_b32 s0, v251, 21
	v_readlane_b32 s1, v251, 22
	s_cmp_gt_i32 s1, 7
	s_cselect_b64 s[2:3], -1, 0
	s_and_b64 s[0:1], s[4:5], s[2:3]
	s_andn2_b64 vcc, exec, s[0:1]
	s_cbranch_vccnz .LBB0_823
	v_and_b32_e32 v2, 0x3fffffff, v0
	v_cmp_eq_u32_e32 vcc, 0, v2
	s_barrier
	s_add_i32 s99, s99, 1
	s_and_saveexec_b64 s[0:1], vcc
	s_cbranch_execz .Lgs6_done
	v_readlane_b32 s4, v251, 15
	v_readlane_b32 s5, v251, 16
	s_add_u32 s4, s4, 0x3940000
	s_addc_u32 s5, s5, 0
	buffer_wbl2 sc1
	s_waitcnt vmcnt(0)
	v_readlane_b32 s6, v251, 0
	s_and_b32 s6, s6, 7
	s_sub_i32 s7, s98, s6
	s_add_i32 s7, s7, 7
	s_lshr_b32 s7, s7, 3
	s_lshl_b32 s6, s6, 12
	s_add_i32 s6, s6, 0x1000
	v_mov_b32_e32 v2, s6
	v_mov_b32_e32 v3, 1
	global_atomic_add v3, v2, v3, s[4:5] sc0
	s_mul_i32 s6, s99, s7
	s_waitcnt vmcnt(0)
	v_readfirstlane_b32 s7, v3
	s_add_i32 s7, s7, 1
	v_mov_b32_e32 v2, 0
	v_mov_b32_e32 v3, 1
	s_cmp_lg_u32 s7, s6
	s_cbranch_scc1 .Lgs6_nolast
	global_atomic_add v2, v3, s[4:5]

; #define RUNPH(n, body)                                   \
;   if (DUP_PH == (n) && DUP_PH == 10) { phase10<true>(p, smem, bid, nb); __syncthreads(); } \
;   if (PHON(n) && lo <= (n) && (n) < hi) { for (int rep = 0; rep < ((DUP_PH == (n) && DUP_PH != 10) ? hi - 9 : 1); rep++) { body; __syncthreads(); } }         \
;   if (lo <= (n) && (n) + 1 < hi) cg::this_grid().sync();
; __global__ void __launch_bounds__(NT) mega(P p, int lo, int hi) {
;     ...
;   RUNPH(7, phase7(p, smem, bid, nb))
.LBB0_849:
	v_readlane_b32 s2, v251, 21
	v_readlane_b32 s3, v251, 22
	s_cmp_gt_i32 s3, 8
	s_cselect_b64 s[2:3], -1, 0
	s_and_b64 s[0:1], s[0:1], s[2:3]
	s_andn2_b64 vcc, exec, s[0:1]
	s_cbranch_vccnz .LBB0_861
	v_and_b32_e32 v2, 0x3fffffff, v0
	v_cmp_eq_u32_e32 vcc, 0, v2
	s_barrier
	s_add_i32 s99, s99, 1
	s_and_saveexec_b64 s[0:1], vcc
	s_cbranch_execz .Lgs7_done
	v_readlane_b32 s4, v251, 15
	v_readlane_b32 s5, v251, 16
	s_add_u32 s4, s4, 0x3940000
	s_addc_u32 s5, s5, 0
	buffer_wbl2 sc1
	s_waitcnt vmcnt(0)
	v_readlane_b32 s6, v251, 0
	s_and_b32 s6, s6, 7
	s_sub_i32 s7, s98, s6
	s_add_i32 s7, s7, 7
	s_lshr_b32 s7, s7, 3
	s_lshl_b32 s6, s6, 12
	s_add_i32 s6, s6, 0x1000
	v_mov_b32_e32 v2, s6
	v_mov_b32_e32 v3, 1
	global_atomic_add v3, v2, v3, s[4:5] sc0
	s_mul_i32 s6, s99, s7
	s_waitcnt vmcnt(0)
	v_readfirstlane_b32 s7, v3
	s_add_i32 s7, s7, 1
	v_mov_b32_e32 v2, 0
	v_mov_b32_e32 v3, 1
	s_cmp_lg_u32 s7, s6
	s_cbranch_scc1 .Lgs7_nolast
	global_atomic_add v2, v3, s[4:5]

; #define RUNPH(n, body)                                   \
;   if (DUP_PH == (n) && DUP_PH == 10) { phase10<true>(p, smem, bid, nb); __syncthreads(); } \
;   if (PHON(n) && lo <= (n) && (n) < hi) { for (int rep = 0; rep < ((DUP_PH == (n) && DUP_PH != 10) ? hi - 9 : 1); rep++) { body; __syncthreads(); } }         \
;   if (lo <= (n) && (n) + 1 < hi) cg::this_grid().sync();
; __global__ void __launch_bounds__(NT) mega(P p, int lo, int hi) {
;     ...
;   RUNPH(8, phase8(p, bid, nb))
.LBB0_866:
	v_readlane_b32 s2, v251, 21
	v_readlane_b32 s3, v251, 22
	s_cmp_gt_i32 s3, 9
	s_cselect_b64 s[2:3], -1, 0
	s_and_b64 s[0:1], s[0:1], s[2:3]
	s_andn2_b64 vcc, exec, s[0:1]
	s_cbranch_vccnz .LBB0_878
	v_and_b32_e32 v2, 0x3fffffff, v0
	v_cmp_eq_u32_e32 vcc, 0, v2
	s_barrier
	s_add_i32 s99, s99, 1
	s_and_saveexec_b64 s[0:1], vcc
	s_cbranch_execz .Lgs8_done
	v_readlane_b32 s4, v251, 15
	v_readlane_b32 s5, v251, 16
	s_add_u32 s4, s4, 0x3940000
	s_addc_u32 s5, s5, 0
	buffer_wbl2 sc1
	s_waitcnt vmcnt(0)
	v_readlane_b32 s6, v251, 0
	s_and_b32 s6, s6, 7
	s_sub_i32 s7, s98, s6
	s_add_i32 s7, s7, 7
	s_lshr_b32 s7, s7, 3
	s_lshl_b32 s6, s6, 12
	s_add_i32 s6, s6, 0x1000
	v_mov_b32_e32 v2, s6
	v_mov_b32_e32 v3, 1
	global_atomic_add v3, v2, v3, s[4:5] sc0
	s_mul_i32 s6, s99, s7
	s_waitcnt vmcnt(0)
	v_readfirstlane_b32 s7, v3
	s_add_i32 s7, s7, 1
	v_mov_b32_e32 v2, 0
	v_mov_b32_e32 v3, 1
	s_cmp_lg_u32 s7, s6
	s_cbranch_scc1 .Lgs8_nolast
	global_atomic_add v2, v3, s[4:5]

; #define RUNPH(n, body)                                   \
;   if (DUP_PH == (n) && DUP_PH == 10) { phase10<true>(p, smem, bid, nb); __syncthreads(); } \
;   if (PHON(n) && lo <= (n) && (n) < hi) { for (int rep = 0; rep < ((DUP_PH == (n) && DUP_PH != 10) ? hi - 9 : 1); rep++) { body; __syncthreads(); } }         \
;   if (lo <= (n) && (n) + 1 < hi) cg::this_grid().sync();
; __global__ void __launch_bounds__(NT) mega(P p, int lo, int hi) {
;     ...
;   RUNPH(9, phase9(p, smem, bid, nb))
.LBB0_900:
	v_readlane_b32 s0, v251, 21
	v_readlane_b32 s1, v251, 22
	s_cmp_gt_i32 s1, 10
	s_cselect_b64 s[0:1], -1, 0
	s_and_b64 s[2:3], s[4:5], s[0:1]
	s_andn2_b64 vcc, exec, s[2:3]
	s_cbranch_vccnz .LBB0_912
	v_and_b32_e32 v2, 0x3fffffff, v0
	v_cmp_eq_u32_e32 vcc, 0, v2
	s_barrier
	s_add_i32 s99, s99, 1
	s_and_saveexec_b64 s[2:3], vcc
	s_cbranch_execz .Lgs9_done
	v_readlane_b32 s4, v251, 15
	v_readlane_b32 s5, v251, 16
	s_add_u32 s4, s4, 0x3940000
	s_addc_u32 s5, s5, 0
	buffer_wbl2 sc1
	s_waitcnt vmcnt(0)
	v_readlane_b32 s6, v251, 0
	s_and_b32 s6, s6, 7
	s_sub_i32 s7, s98, s6
	s_add_i32 s7, s7, 7
	s_lshr_b32 s7, s7, 3
	s_lshl_b32 s6, s6, 12
	s_add_i32 s6, s6, 0x1000
	v_mov_b32_e32 v2, s6
	v_mov_b32_e32 v3, 1
	global_atomic_add v3, v2, v3, s[4:5] sc0
	s_mul_i32 s6, s99, s7
	s_waitcnt vmcnt(0)
	v_readfirstlane_b32 s7, v3
	s_add_i32 s7, s7, 1
	v_mov_b32_e32 v2, 0
	v_mov_b32_e32 v3, 1
	s_cmp_lg_u32 s7, s6
	s_cbranch_scc1 .Lgs9_nolast
	global_atomic_add v2, v3, s[4:5]
